# DN gate prefix-sum via DPP row_shr/row_bcast instead of 6 ds_bpermute round trips
# speedup vs baseline: 1.0349x; 1.0131x over previous
; DI float sigmoidf_(float x) { return __builtin_amdgcn_rcpf(1.f + __expf(-x)); }
; DI float softplusf_(float x) { return x > 20.f ? x : log1pf(expf(x)); }
; template <bool CONS>
; DI void dn_chain_role(const Params& p, unsigned char* smem, int dir, int b, int h) {
;     ...
;             const float beta = sigmoidf_(pbr), g = -a_coef * softplusf_(par + dtb);
;             float G = g;
; #pragma unroll
;             for (int o = 1; o < 64; o <<= 1) { const float t = __shfl_up(G, o); if (lane >= o) G += t; }
;             const float Gl = __shfl(G, 63), eG = expf(G);
;             sG[lane] = G * 1.4426950408889634f; sBeta[lane] = beta; sEG[lane] = eG; sDL[lane] = expf(Gl - G); sRow[lane] = prow;
.LBB0_525:
	s_or_b64 exec, exec, s[8:9]
	v_mul_f32_e64 v5, v5, -v134
	v_mul_f32_e32 v7, 0xbfb8aa3b, v132
	v_exp_f32_e32 v7, v7
	v_add_f32_dpp v5, v5, v5 row_shr:1 row_mask:0xf bank_mask:0xf
	v_add_f32_e32 v7, 1.0, v7
	s_nop 0
	v_add_f32_dpp v5, v5, v5 row_shr:2 row_mask:0xf bank_mask:0xf
	v_rcp_f32_e32 v7, v7
	s_nop 0
	v_add_f32_dpp v5, v5, v5 row_shr:4 row_mask:0xf bank_mask:0xf
	s_nop 1
	v_add_f32_dpp v5, v5, v5 row_shr:8 row_mask:0xf bank_mask:0xf
	s_nop 1
	v_add_f32_dpp v5, v5, v5 row_bcast:15 row_mask:0xa bank_mask:0xf
	s_nop 1
	v_add_f32_dpp v5, v5, v5 row_bcast:31 row_mask:0xc bank_mask:0xf
	v_mul_f32_e32 v6, 0x3fb8aa3b, v5
	v_fma_f32 v8, v5, s38, -v6
	v_rndne_f32_e32 v9, v6
	v_fmac_f32_e32 v8, 0x32a5705f, v5
	v_sub_f32_e32 v10, v6, v9
	v_add_f32_e32 v8, v10, v8
	ds_bpermute_b32 v10, v137, v5
	v_exp_f32_e32 v8, v8
	v_cvt_i32_f32_e32 v9, v9
	v_cmp_ngt_f32_e32 vcc, s39, v5
	v_ldexp_f32 v8, v8, v9
	s_waitcnt lgkmcnt(0)
	v_sub_f32_e32 v9, v10, v5
	v_mul_f32_e32 v10, 0x3fb8aa3b, v9
	v_fma_f32 v11, v9, s38, -v10
	v_rndne_f32_e32 v12, v10
	v_fmac_f32_e32 v11, 0x32a5705f, v9
	v_sub_f32_e32 v10, v10, v12
	v_add_f32_e32 v10, v10, v11
	v_exp_f32_e32 v10, v10
	v_cvt_i32_f32_e32 v11, v12
	v_cndmask_b32_e32 v8, 0, v8, vcc
	v_cmp_nlt_f32_e32 vcc, s40, v5
	s_nop 1
	v_cndmask_b32_e32 v5, v133, v8, vcc
	v_lshl_add_u32 v8, v138, 2, s78
	ds_write2st64_b32 v8, v6, v7 offset1:1
	v_ldexp_f32 v6, v10, v11
	v_cmp_ngt_f32_e32 vcc, s39, v9
	s_nop 1
	v_cndmask_b32_e32 v6, 0, v6, vcc
	v_cmp_nlt_f32_e32 vcc, s40, v9
	s_nop 1
	v_cndmask_b32_e32 v6, v133, v6, vcc
	ds_write2st64_b32 v8, v5, v6 offset0:2 offset1:3
	ds_write_b32 v8, v124 offset:1280
